# v51 + norm1/norm2 row loops: row-invariant gain vector loaded once per wave before the loop
# speedup vs baseline: 1.1042x; 1.1042x over previous
.LBB0_130:
	s_andn2_b64 vcc, exec, s[40:41]
	s_cbranch_vccnz .LBB0_137
	s_waitcnt vmcnt(0) lgkmcnt(0)
	v_mov_b32_e32 v11, v168
	v_mov_b32_e32 v0, v168
	v_readlane_b32 s0, v254, 7
	v_ashrrev_i32_e32 v10, 6, v0
	s_nop 0
	v_add_u32_e32 v8, s0, v10
	v_readlane_b32 s0, v254, 46
	v_readlane_b32 s1, v254, 47
	s_movk_i32 s1, 0x3000
	s_nop 0
	v_cmp_gt_i32_e32 vcc, s1, v8
	s_and_saveexec_b64 s[40:41], vcc
	s_cbranch_execz .LBB0_136
	v_ashrrev_i32_e32 v9, 31, v8
	v_readlane_b32 s44, v254, 48
	v_lshlrev_b32_e32 v3, 2, v11
	v_lshlrev_b64 v[0:1], 12, v[8:9]
	v_readlane_b32 s46, v254, 50
	v_readlane_b32 s47, v254, 51
	v_and_b32_e32 v12, 0xfc, v3
	v_lshlrev_b32_e32 v14, 2, v12
	v_lshl_add_u64 v[0:1], s[46:47], 0, v[0:1]
	v_mov_b32_e32 v15, v2
	v_lshl_add_u64 v[0:1], v[0:1], 0, v[14:15]
	global_load_dwordx4 v[32:35], v[0:1], off
	global_load_dwordx4 v[28:31], v[0:1], off offset:1024
	global_load_dwordx4 v[24:27], v[0:1], off offset:2048
	global_load_dwordx4 v[4:7], v[0:1], off offset:3072
	v_lshlrev_b64 v[8:9], 11, v[8:9]
	v_and_b32_e32 v11, 63, v11
	v_readlane_b32 s0, v252, 32
	v_lshl_or_b32 v8, v11, 3, v8
	v_readlane_b32 s1, v252, 33
	v_cmp_lt_i32_e32 vcc, v180, v182
	s_add_u32 s2, s14, s38
	v_lshl_add_u64 v[36:37], s[0:1], 0, v[8:9]
	v_readlane_b32 s0, v254, 8
	v_cndmask_b32_e32 v0, v179, v180, vcc
	v_cmp_lt_i32_e32 vcc, v183, v182
	v_add_u32_e32 v41, s0, v10
	v_readlane_b32 s0, v254, 2
	v_lshlrev_b32_e32 v3, 2, v0
	v_cndmask_b32_e32 v0, v179, v183, vcc
	v_add_u32_e32 v8, s0, v10
	v_cmp_lt_i32_e32 vcc, v184, v182
	v_ashrrev_i32_e32 v9, 31, v8
	v_lshlrev_b32_e32 v49, 2, v0
	v_cndmask_b32_e32 v0, v179, v184, vcc
	v_cmp_lt_i32_e32 vcc, v185, v182
	v_lshlrev_b64 v[8:9], 12, v[8:9]
	v_readlane_b32 s0, v250, 51
	v_lshlrev_b32_e32 v54, 2, v0
	v_cndmask_b32_e32 v0, v179, v185, vcc
	v_cmp_lt_i32_e32 vcc, v186, v182
	v_lshl_or_b32 v8, v11, 4, v8
	v_readlane_b32 s1, v250, 52
	v_lshlrev_b32_e32 v55, 2, v0
	v_cndmask_b32_e32 v0, v179, v186, vcc
	v_cmp_lt_i32_e32 vcc, v187, v182
	v_lshl_add_u64 v[38:39], s[0:1], 0, v[8:9]
	v_readlane_b32 s0, v254, 46
	s_addc_u32 s3, s15, s39
	v_lshlrev_b32_e32 v56, 2, v0
	v_cndmask_b32_e32 v0, v179, v187, vcc
	v_or_b32_e32 v16, 0x100, v12
	v_or_b32_e32 v18, 0x200, v12
	v_or_b32_e32 v20, 0x300, v12
	v_readlane_b32 s1, v254, 47
	v_lshlrev_b32_e32 v57, 2, v0
	v_lshl_add_u64 v[0:1], s[2:3], 0, v[14:15]
	global_load_dwordx4 v[100:103], v[0:1], off
	global_load_dwordx4 v[104:107], v[0:1], off offset:1024
	global_load_dwordx4 v[108:111], v[0:1], off offset:2048
	global_load_dwordx4 v[112:115], v[0:1], off offset:3072
	s_movk_i32 s1, 0x3000
	s_mov_b64 s[38:39], 0
	v_lshlrev_b32_e32 v40, 2, v12
	v_lshlrev_b32_e32 v42, 2, v16
	v_lshlrev_b32_e32 v44, 2, v18
	v_lshlrev_b32_e32 v46, 2, v20
	v_readlane_b32 s45, v254, 49
	v_readlane_b32 s48, v254, 52
	v_readlane_b32 s49, v254, 53
	v_readlane_b32 s50, v254, 54
	v_readlane_b32 s51, v254, 55
	s_branch .LBB0_134
.LBB0_133:
	s_or_b64 exec, exec, s[42:43]
	s_and_b64 s[2:3], exec, vcc
	s_or_b64 s[38:39], s[2:3], s[38:39]
	v_add_u32_e32 v43, 0x1000, v41
	v_lshrrev_b32_e32 v41, 11, v41
	s_movk_i32 s2, 0xfff
	v_add_u32_e32 v41, 1, v41
	v_cmp_lt_i32_e32 vcc, s2, v43
	v_readlane_b32 s2, v254, 61
	v_readlane_b32 s3, v254, 62
	v_cndmask_b32_e32 v41, 0, v41, vcc
	s_mul_i32 s2, s2, 5
	v_add_u32_e32 v41, s2, v41
	v_readlane_b32 s2, v252, 36
	v_readlane_b32 s3, v252, 37
	s_nop 0
	v_mul_f32_e32 v45, v33, v33
	v_mov_b64_e32 v[50:51], s[2:3]
	v_mad_i64_i32 v[52:53], s[2:3], v41, s97, v[50:51]
	s_mov_b64 s[2:3], 0x1000
	s_nop 0
	v_lshl_add_u64 v[50:51], v[52:53], 0, s[2:3]
	v_mov_b32_e32 v41, v2
	v_lshl_add_u64 v[52:53], v[52:53], 0, v[40:41]
	v_lshl_add_u64 v[68:69], v[50:51], 0, v[40:41]
	global_load_dwordx4 v[64:67], v[52:53], off
	v_mul_f32_e32 v47, v29, v29
	global_load_dwordx4 v[68:71], v[68:69], off
	v_fmac_f32_e32 v45, v32, v32
	v_fmac_f32_e32 v47, v28, v28
	v_fmac_f32_e32 v45, v34, v34
	v_fmac_f32_e32 v47, v30, v30
	v_fmac_f32_e32 v45, v35, v35
	v_fmac_f32_e32 v47, v31, v31
	v_add_f32_e32 v45, v45, v47
	v_mul_f32_e32 v47, v25, v25
	v_fmac_f32_e32 v47, v24, v24
	v_fmac_f32_e32 v47, v26, v26
	v_fmac_f32_e32 v47, v27, v27
	v_add_f32_e32 v45, v47, v45
	v_mul_f32_e32 v47, v5, v5
	v_fmac_f32_e32 v47, v4, v4
	v_fmac_f32_e32 v47, v6, v6
	v_fmac_f32_e32 v47, v7, v7
	v_add_f32_e32 v45, v47, v45
	ds_bpermute_b32 v47, v3, v45
	v_mov_b32_e32 v43, v2
	v_readlane_b32 s2, v254, 11
	v_readlane_b32 s3, v254, 12
	v_mov_b32_e32 v41, v58
	s_waitcnt lgkmcnt(0)
	v_add_f32_e32 v45, v45, v47
	ds_bpermute_b32 v47, v49, v45
	s_waitcnt lgkmcnt(0)
	v_add_f32_e32 v45, v45, v47
	ds_bpermute_b32 v47, v54, v45
	s_waitcnt lgkmcnt(0)
	v_add_f32_e32 v45, v45, v47
	ds_bpermute_b32 v47, v55, v45
	s_waitcnt lgkmcnt(0)
	v_add_f32_e32 v45, v45, v47
	ds_bpermute_b32 v47, v56, v45
	s_waitcnt lgkmcnt(0)
	v_add_f32_e32 v45, v45, v47
	ds_bpermute_b32 v47, v57, v45
	s_waitcnt lgkmcnt(0)
	v_add_f32_e32 v45, v45, v47
	v_fmamk_f32 v45, v45, 0x3a800000, v174
	v_rsq_f32_e32 v48, v45
	v_mov_b32_e32 v45, v2
	v_mov_b32_e32 v47, v2
	v_pk_mul_f32 v[34:35], v[34:35], v[48:49] op_sel_hi:[1,0]
	v_pk_mul_f32 v[32:33], v[32:33], v[48:49] op_sel_hi:[1,0]
	v_pk_mul_f32 v[30:31], v[30:31], v[48:49] op_sel_hi:[1,0]
	v_pk_mul_f32 v[28:29], v[28:29], v[48:49] op_sel_hi:[1,0]
	v_pk_mul_f32 v[26:27], v[26:27], v[48:49] op_sel_hi:[1,0]
	v_pk_mul_f32 v[24:25], v[24:25], v[48:49] op_sel_hi:[1,0]
	v_pk_mul_f32 v[6:7], v[6:7], v[48:49] op_sel_hi:[1,0]
	v_pk_mul_f32 v[4:5], v[4:5], v[48:49] op_sel_hi:[1,0]
	s_nop 0
	v_pk_mul_f32 v[32:33], v[100:101], v[32:33]
	v_pk_mul_f32 v[34:35], v[102:103], v[34:35]
	s_waitcnt vmcnt(0)
	v_pk_add_f32 v[60:61], v[70:71], 1.0 op_sel_hi:[1,0]
	v_pk_add_f32 v[62:63], v[68:69], 1.0 op_sel_hi:[1,0]
	v_pk_fma_f32 v[34:35], v[60:61], v[34:35], v[66:67]
	v_pk_fma_f32 v[32:33], v[62:63], v[32:33], v[64:65]
	v_lshl_add_u64 v[64:65], v[50:51], 0, v[42:43]
	v_cvt_pk_bf16_f32 v32, v32, v33
	v_cvt_pk_bf16_f32 v33, v34, v35
	global_store_dwordx2 v[36:37], v[32:33], off
	s_nop 0
	s_nop 0
	global_load_dwordx4 v[60:63], v[52:53], off offset:1024
	s_nop 0
	v_pk_mul_f32 v[28:29], v[104:105], v[28:29]
	global_load_dwordx4 v[64:67], v[64:65], off
	v_pk_mul_f32 v[30:31], v[106:107], v[30:31]
	s_waitcnt vmcnt(0)
	v_pk_add_f32 v[32:33], v[66:67], 1.0 op_sel_hi:[1,0]
	v_pk_add_f32 v[34:35], v[64:65], 1.0 op_sel_hi:[1,0]
	v_pk_fma_f32 v[30:31], v[32:33], v[30:31], v[62:63]
	v_pk_fma_f32 v[28:29], v[34:35], v[28:29], v[60:61]
	v_lshl_add_u64 v[60:61], v[50:51], 0, v[44:45]
	v_cvt_pk_bf16_f32 v28, v28, v29
	v_cvt_pk_bf16_f32 v29, v30, v31
	global_store_dwordx2 v[36:37], v[28:29], off offset:512
	s_nop 0
	s_nop 0
	global_load_dwordx4 v[32:35], v[52:53], off offset:2048
	s_nop 0
	v_pk_mul_f32 v[24:25], v[24:25], v[108:109]
	global_load_dwordx4 v[60:63], v[60:61], off
	v_pk_mul_f32 v[26:27], v[26:27], v[110:111]
	s_waitcnt vmcnt(0)
	v_pk_add_f32 v[28:29], v[62:63], 1.0 op_sel_hi:[1,0]
	v_pk_add_f32 v[30:31], v[60:61], 1.0 op_sel_hi:[1,0]
	v_pk_fma_f32 v[26:27], v[26:27], v[28:29], v[34:35]
	v_pk_fma_f32 v[24:25], v[24:25], v[30:31], v[32:33]
	v_lshl_add_u64 v[32:33], v[50:51], 0, v[46:47]
	v_cvt_pk_bf16_f32 v24, v24, v25
	v_cvt_pk_bf16_f32 v25, v26, v27
	global_store_dwordx2 v[36:37], v[24:25], off offset:1024
	s_nop 0
	s_nop 0
	global_load_dwordx4 v[28:31], v[52:53], off offset:3072
	s_nop 0
	v_pk_mul_f32 v[4:5], v[4:5], v[112:113]
	global_load_dwordx4 v[32:35], v[32:33], off
	v_pk_mul_f32 v[6:7], v[6:7], v[114:115]
	s_waitcnt vmcnt(0)
	v_pk_add_f32 v[24:25], v[34:35], 1.0 op_sel_hi:[1,0]
	v_pk_add_f32 v[26:27], v[32:33], 1.0 op_sel_hi:[1,0]
	v_pk_fma_f32 v[6:7], v[6:7], v[24:25], v[30:31]
	v_pk_fma_f32 v[4:5], v[4:5], v[26:27], v[28:29]
	v_mov_b32_e32 v32, v12
	v_cvt_pk_bf16_f32 v4, v4, v5
	v_cvt_pk_bf16_f32 v5, v6, v7
	global_store_dwordx2 v[36:37], v[4:5], off offset:1536
	v_lshl_add_u64 v[36:37], v[36:37], 0, s[2:3]
	v_readlane_b32 s2, v254, 9
	v_readlane_b32 s3, v254, 10
	v_mov_b32_e32 v33, v13
	v_mov_b32_e32 v34, v14
	v_lshl_add_u64 v[38:39], v[38:39], 0, s[2:3]
	v_mov_b32_e32 v35, v15
	v_mov_b32_e32 v28, v16
	v_mov_b32_e32 v29, v17
	v_mov_b32_e32 v30, v18
	v_mov_b32_e32 v31, v19
	v_mov_b32_e32 v24, v20
	v_mov_b32_e32 v25, v21
	v_mov_b32_e32 v26, v22
	v_mov_b32_e32 v27, v23
	v_mov_b32_e32 v4, v8
	v_mov_b32_e32 v5, v9
	v_mov_b32_e32 v6, v10
	v_mov_b32_e32 v7, v11
	s_andn2_b64 exec, exec, s[38:39]
	s_cbranch_execz .LBB0_136

.LBB0_177:
	s_or_b64 exec, exec, s[36:37]
	v_mov_b32_e32 v11, v168
	v_mov_b32_e32 v0, v168
	v_readlane_b32 s0, v254, 7
	v_ashrrev_i32_e32 v10, 6, v0
	s_nop 0
	v_add_u32_e32 v8, s0, v10
	v_cmp_gt_i32_e32 vcc, s1, v8
	s_and_saveexec_b64 s[38:39], vcc
	v_readlane_b32 s0, v254, 46
	v_readlane_b32 s1, v254, 47
	s_cbranch_execz .LBB0_182
	v_ashrrev_i32_e32 v9, 31, v8
	v_readlane_b32 s40, v254, 48
	v_lshlrev_b32_e32 v3, 2, v11
	v_lshlrev_b64 v[0:1], 12, v[8:9]
	v_readlane_b32 s42, v254, 50
	v_readlane_b32 s43, v254, 51
	v_and_b32_e32 v12, 0xfc, v3
	v_lshlrev_b32_e32 v14, 2, v12
	v_lshl_add_u64 v[0:1], s[42:43], 0, v[0:1]
	v_mov_b32_e32 v15, v2
	v_lshl_add_u64 v[0:1], v[0:1], 0, v[14:15]
	global_load_dwordx4 v[32:35], v[0:1], off
	global_load_dwordx4 v[28:31], v[0:1], off offset:1024
	global_load_dwordx4 v[24:27], v[0:1], off offset:2048
	global_load_dwordx4 v[4:7], v[0:1], off offset:3072
	v_cmp_lt_i32_e32 vcc, v180, v182
	v_readlane_b32 s0, v255, 0
	v_readlane_b32 s1, v255, 1
	v_cndmask_b32_e32 v0, v179, v180, vcc
	v_cmp_lt_i32_e32 vcc, v183, v182
	v_lshlrev_b32_e32 v3, 2, v0
	v_lshlrev_b64 v[8:9], 11, v[8:9]
	v_cndmask_b32_e32 v0, v179, v183, vcc
	v_cmp_lt_i32_e32 vcc, v184, v182
	v_lshlrev_b32_e32 v49, 2, v0
	v_and_b32_e32 v11, 63, v11
	v_cndmask_b32_e32 v0, v179, v184, vcc
	v_cmp_lt_i32_e32 vcc, v185, v182
	v_lshlrev_b32_e32 v54, 2, v0
	v_lshl_or_b32 v8, v11, 3, v8
	v_cndmask_b32_e32 v0, v179, v185, vcc
	v_cmp_lt_i32_e32 vcc, v186, v182
	v_lshlrev_b32_e32 v55, 2, v0
	v_readlane_b32 s41, v254, 49
	v_cndmask_b32_e32 v0, v179, v186, vcc
	v_cmp_lt_i32_e32 vcc, v187, v182
	v_lshlrev_b32_e32 v56, 2, v0
	v_or_b32_e32 v16, 0x100, v12
	v_cndmask_b32_e32 v0, v179, v187, vcc
	v_lshlrev_b32_e32 v57, 2, v0
	v_lshl_add_u64 v[0:1], s[0:1], 0, v[14:15]
	global_load_dwordx4 v[100:103], v[0:1], off
	global_load_dwordx4 v[104:107], v[0:1], off offset:1024
	global_load_dwordx4 v[108:111], v[0:1], off offset:2048
	global_load_dwordx4 v[112:115], v[0:1], off offset:3072
	v_readlane_b32 s0, v252, 32
	v_readlane_b32 s1, v252, 33
	v_or_b32_e32 v18, 0x200, v12
	v_or_b32_e32 v20, 0x300, v12
	v_lshl_add_u64 v[36:37], s[0:1], 0, v[8:9]
	v_readlane_b32 s0, v254, 8
	s_mov_b64 s[40:41], 0
	v_lshlrev_b32_e32 v40, 2, v12
	v_add_u32_e32 v41, s0, v10
	v_readlane_b32 s0, v254, 2
	v_lshlrev_b32_e32 v42, 2, v16
	v_lshlrev_b32_e32 v44, 2, v18
	v_add_u32_e32 v8, s0, v10
	v_ashrrev_i32_e32 v9, 31, v8
	v_lshlrev_b64 v[8:9], 12, v[8:9]
	v_readlane_b32 s0, v250, 51
	v_lshl_or_b32 v8, v11, 4, v8
	v_readlane_b32 s1, v250, 52
	v_lshlrev_b32_e32 v46, 2, v20
	v_readlane_b32 s44, v254, 52
	v_lshl_add_u64 v[38:39], s[0:1], 0, v[8:9]
	v_readlane_b32 s0, v254, 46
	v_readlane_b32 s1, v254, 47
	s_movk_i32 s1, 0x3000
	v_readlane_b32 s45, v254, 53
	v_readlane_b32 s46, v254, 54
	v_readlane_b32 s47, v254, 55
	s_branch .LBB0_180
.LBB0_179:
	s_or_b64 exec, exec, s[42:43]
	s_and_b64 s[2:3], exec, vcc
	s_or_b64 s[40:41], s[2:3], s[40:41]
	v_add_u32_e32 v43, 0x1000, v41
	v_lshrrev_b32_e32 v41, 11, v41
	s_movk_i32 s2, 0xfff
	v_add_u32_e32 v41, 1, v41
	v_cmp_lt_i32_e32 vcc, s2, v43
	v_readlane_b32 s2, v254, 61
	v_readlane_b32 s3, v254, 62
	v_cndmask_b32_e32 v41, 0, v41, vcc
	s_mul_i32 s2, s2, 5
	v_add_u32_e32 v41, s2, v41
	v_readlane_b32 s2, v251, 63
	v_readlane_b32 s3, v252, 0
	s_nop 0
	v_mul_f32_e32 v45, v33, v33
	v_mov_b64_e32 v[50:51], s[2:3]
	v_mad_i64_i32 v[52:53], s[2:3], v41, s97, v[50:51]
	s_mov_b64 s[2:3], 0x1000
	s_nop 0
	v_lshl_add_u64 v[50:51], v[52:53], 0, s[2:3]
	v_mov_b32_e32 v41, v2
	v_lshl_add_u64 v[52:53], v[52:53], 0, v[40:41]
	v_lshl_add_u64 v[68:69], v[50:51], 0, v[40:41]
	global_load_dwordx4 v[64:67], v[52:53], off
	v_mul_f32_e32 v47, v29, v29
	global_load_dwordx4 v[68:71], v[68:69], off
	v_fmac_f32_e32 v45, v32, v32
	v_fmac_f32_e32 v47, v28, v28
	v_fmac_f32_e32 v45, v34, v34
	v_fmac_f32_e32 v47, v30, v30
	v_fmac_f32_e32 v45, v35, v35
	v_fmac_f32_e32 v47, v31, v31
	v_add_f32_e32 v45, v45, v47
	v_mul_f32_e32 v47, v25, v25
	v_fmac_f32_e32 v47, v24, v24
	v_fmac_f32_e32 v47, v26, v26
	v_fmac_f32_e32 v47, v27, v27
	v_add_f32_e32 v45, v47, v45
	v_mul_f32_e32 v47, v5, v5
	v_fmac_f32_e32 v47, v4, v4
	v_fmac_f32_e32 v47, v6, v6
	v_fmac_f32_e32 v47, v7, v7
	v_add_f32_e32 v45, v47, v45
	ds_bpermute_b32 v47, v3, v45
	v_mov_b32_e32 v43, v2
	v_readlane_b32 s2, v254, 11
	v_readlane_b32 s3, v254, 12
	v_mov_b32_e32 v41, v58
	s_waitcnt lgkmcnt(0)
	v_add_f32_e32 v45, v45, v47
	ds_bpermute_b32 v47, v49, v45
	s_waitcnt lgkmcnt(0)
	v_add_f32_e32 v45, v45, v47
	ds_bpermute_b32 v47, v54, v45
	s_waitcnt lgkmcnt(0)
	v_add_f32_e32 v45, v45, v47
	ds_bpermute_b32 v47, v55, v45
	s_waitcnt lgkmcnt(0)
	v_add_f32_e32 v45, v45, v47
	ds_bpermute_b32 v47, v56, v45
	s_waitcnt lgkmcnt(0)
	v_add_f32_e32 v45, v45, v47
	ds_bpermute_b32 v47, v57, v45
	s_waitcnt lgkmcnt(0)
	v_add_f32_e32 v45, v45, v47
	v_fmamk_f32 v45, v45, 0x3a800000, v174
	v_rsq_f32_e32 v48, v45
	v_mov_b32_e32 v45, v2
	v_mov_b32_e32 v47, v2
	v_pk_mul_f32 v[34:35], v[34:35], v[48:49] op_sel_hi:[1,0]
	v_pk_mul_f32 v[32:33], v[32:33], v[48:49] op_sel_hi:[1,0]
	v_pk_mul_f32 v[30:31], v[30:31], v[48:49] op_sel_hi:[1,0]
	v_pk_mul_f32 v[28:29], v[28:29], v[48:49] op_sel_hi:[1,0]
	v_pk_mul_f32 v[26:27], v[26:27], v[48:49] op_sel_hi:[1,0]
	v_pk_mul_f32 v[24:25], v[24:25], v[48:49] op_sel_hi:[1,0]
	v_pk_mul_f32 v[6:7], v[6:7], v[48:49] op_sel_hi:[1,0]
	v_pk_mul_f32 v[4:5], v[4:5], v[48:49] op_sel_hi:[1,0]
	s_nop 0
	v_pk_mul_f32 v[32:33], v[100:101], v[32:33]
	v_pk_mul_f32 v[34:35], v[102:103], v[34:35]
	s_waitcnt vmcnt(0)
	v_pk_add_f32 v[60:61], v[70:71], 1.0 op_sel_hi:[1,0]
	v_pk_add_f32 v[62:63], v[68:69], 1.0 op_sel_hi:[1,0]
	v_pk_fma_f32 v[34:35], v[60:61], v[34:35], v[66:67]
	v_pk_fma_f32 v[32:33], v[62:63], v[32:33], v[64:65]
	v_lshl_add_u64 v[64:65], v[50:51], 0, v[42:43]
	v_cvt_pk_bf16_f32 v32, v32, v33
	v_cvt_pk_bf16_f32 v33, v34, v35
	global_store_dwordx2 v[36:37], v[32:33], off
	s_nop 0
	s_nop 0
	global_load_dwordx4 v[60:63], v[52:53], off offset:1024
	s_nop 0
	v_pk_mul_f32 v[28:29], v[104:105], v[28:29]
	global_load_dwordx4 v[64:67], v[64:65], off
	v_pk_mul_f32 v[30:31], v[106:107], v[30:31]
	s_waitcnt vmcnt(0)
	v_pk_add_f32 v[32:33], v[66:67], 1.0 op_sel_hi:[1,0]
	v_pk_add_f32 v[34:35], v[64:65], 1.0 op_sel_hi:[1,0]
	v_pk_fma_f32 v[30:31], v[32:33], v[30:31], v[62:63]
	v_pk_fma_f32 v[28:29], v[34:35], v[28:29], v[60:61]
	v_lshl_add_u64 v[60:61], v[50:51], 0, v[44:45]
	v_cvt_pk_bf16_f32 v28, v28, v29
	v_cvt_pk_bf16_f32 v29, v30, v31
	global_store_dwordx2 v[36:37], v[28:29], off offset:512
	s_nop 0
	s_nop 0
	global_load_dwordx4 v[32:35], v[52:53], off offset:2048
	s_nop 0
	v_pk_mul_f32 v[24:25], v[24:25], v[108:109]
	global_load_dwordx4 v[60:63], v[60:61], off
	v_pk_mul_f32 v[26:27], v[26:27], v[110:111]
	s_waitcnt vmcnt(0)
	v_pk_add_f32 v[28:29], v[62:63], 1.0 op_sel_hi:[1,0]
	v_pk_add_f32 v[30:31], v[60:61], 1.0 op_sel_hi:[1,0]
	v_pk_fma_f32 v[26:27], v[26:27], v[28:29], v[34:35]
	v_pk_fma_f32 v[24:25], v[24:25], v[30:31], v[32:33]
	v_lshl_add_u64 v[32:33], v[50:51], 0, v[46:47]
	v_cvt_pk_bf16_f32 v24, v24, v25
	v_cvt_pk_bf16_f32 v25, v26, v27
	global_store_dwordx2 v[36:37], v[24:25], off offset:1024
	s_nop 0
	s_nop 0
	global_load_dwordx4 v[28:31], v[52:53], off offset:3072
	s_nop 0
	v_pk_mul_f32 v[4:5], v[4:5], v[112:113]
	global_load_dwordx4 v[32:35], v[32:33], off
	v_pk_mul_f32 v[6:7], v[6:7], v[114:115]
	s_waitcnt vmcnt(0)
	v_pk_add_f32 v[24:25], v[34:35], 1.0 op_sel_hi:[1,0]
	v_pk_add_f32 v[26:27], v[32:33], 1.0 op_sel_hi:[1,0]
	v_pk_fma_f32 v[6:7], v[6:7], v[24:25], v[30:31]
	v_pk_fma_f32 v[4:5], v[4:5], v[26:27], v[28:29]
	v_mov_b32_e32 v32, v12
	v_cvt_pk_bf16_f32 v4, v4, v5
	v_cvt_pk_bf16_f32 v5, v6, v7
	global_store_dwordx2 v[36:37], v[4:5], off offset:1536
	v_lshl_add_u64 v[36:37], v[36:37], 0, s[2:3]
	v_readlane_b32 s2, v254, 9
	v_readlane_b32 s3, v254, 10
	v_mov_b32_e32 v33, v13
	v_mov_b32_e32 v34, v14
	v_lshl_add_u64 v[38:39], v[38:39], 0, s[2:3]
	v_mov_b32_e32 v35, v15
	v_mov_b32_e32 v28, v16
	v_mov_b32_e32 v29, v17
	v_mov_b32_e32 v30, v18
	v_mov_b32_e32 v31, v19
	v_mov_b32_e32 v24, v20
	v_mov_b32_e32 v25, v21
	v_mov_b32_e32 v26, v22
	v_mov_b32_e32 v27, v23
	v_mov_b32_e32 v4, v8
	v_mov_b32_e32 v5, v9
	v_mov_b32_e32 v6, v10
	v_mov_b32_e32 v7, v11
	s_andn2_b64 exec, exec, s[40:41]
	s_cbranch_execz .LBB0_182
